# final RMSNorm: non-temporal hint on the last-use activation loads (on the full bundle with nt prologue loads)
# speedup vs baseline: 1.0238x; 1.0019x over previous
.LBB0_953:
	s_ashr_i32 s3, s2, 31
	s_lshl_b64 s[4:5], s[2:3], 11
	s_waitcnt vmcnt(4)
	v_lshl_add_u64 v[22:23], v[16:17], 0, s[4:5]
	global_load_dwordx2 v[52:53], v[22:23], off nt
	global_load_dwordx2 v[50:51], v[22:23], off offset:512 nt
	global_load_dwordx2 v[48:49], v[22:23], off offset:1024 nt
	global_load_dwordx2 v[46:47], v[22:23], off offset:1536 nt
	v_mov_b32_e32 v64, 0
	s_and_saveexec_b64 s[4:5], s[0:1]
	s_cbranch_execz .LBB0_955
	s_lshl_b64 s[6:7], s[2:3], 6
	v_lshl_add_u64 v[22:23], v[18:19], 0, s[6:7]
	global_load_dword v64, v[22:23], off nt
.LBB0_955:
	s_or_b64 exec, exec, s[4:5]
	s_add_i32 s4, s2, s55
	s_cmp_lt_i32 s4, s59
	s_cselect_b64 s[14:15], -1, 0
	s_and_b64 s[6:7], s[14:15], exec
	s_cselect_b32 s6, s4, s2
	s_ashr_i32 s7, s6, 31
	s_lshl_b64 s[8:9], s[6:7], 11
	v_lshl_add_u64 v[22:23], v[16:17], 0, s[8:9]
	global_load_dwordx2 v[44:45], v[22:23], off nt
	global_load_dwordx2 v[42:43], v[22:23], off offset:512 nt
	global_load_dwordx2 v[40:41], v[22:23], off offset:1024 nt
	global_load_dwordx2 v[38:39], v[22:23], off offset:1536 nt
	v_mov_b32_e32 v62, 0
	v_mov_b32_e32 v63, 0
	s_and_saveexec_b64 s[8:9], s[0:1]
	s_cbranch_execz .LBB0_957
	s_lshl_b64 s[6:7], s[6:7], 6
	v_lshl_add_u64 v[22:23], v[18:19], 0, s[6:7]
	global_load_dword v63, v[22:23], off nt
.LBB0_957:
	s_or_b64 exec, exec, s[8:9]
	s_add_i32 s10, s20, s2
	s_cmp_lt_i32 s10, s59
	s_cselect_b64 s[12:13], -1, 0
	s_and_b64 s[6:7], s[12:13], exec
	s_cselect_b32 s6, s10, s2
	s_ashr_i32 s7, s6, 31
	s_lshl_b64 s[8:9], s[6:7], 11
	v_lshl_add_u64 v[22:23], v[16:17], 0, s[8:9]
	global_load_dwordx2 v[36:37], v[22:23], off nt
	global_load_dwordx2 v[34:35], v[22:23], off offset:512 nt
	global_load_dwordx2 v[32:33], v[22:23], off offset:1024 nt
	global_load_dwordx2 v[30:31], v[22:23], off offset:1536 nt
	s_and_saveexec_b64 s[8:9], s[0:1]
	s_cbranch_execz .LBB0_959
	s_lshl_b64 s[6:7], s[6:7], 6
	v_lshl_add_u64 v[22:23], v[18:19], 0, s[6:7]
	global_load_dword v62, v[22:23], off nt
.LBB0_959:
	s_or_b64 exec, exec, s[8:9]
	s_add_i32 s6, s60, s2
	s_cmp_lt_i32 s6, s59
	s_cselect_b64 s[8:9], -1, 0
	s_and_b64 s[16:17], s[8:9], exec
	s_cselect_b32 s16, s6, s2
	s_ashr_i32 s17, s16, 31
	s_lshl_b64 s[18:19], s[16:17], 11
	v_lshl_add_u64 v[66:67], v[16:17], 0, s[18:19]
	global_load_dwordx2 v[28:29], v[66:67], off nt
	global_load_dwordx2 v[26:27], v[66:67], off offset:512 nt
	global_load_dwordx2 v[24:25], v[66:67], off offset:1024 nt
	global_load_dwordx2 v[22:23], v[66:67], off offset:1536 nt
	v_mov_b32_e32 v61, 0
	s_and_saveexec_b64 s[18:19], s[0:1]
	s_cbranch_execz .LBB0_961
	s_lshl_b64 s[16:17], s[16:17], 6
	v_lshl_add_u64 v[66:67], v[18:19], 0, s[16:17]
	global_load_dword v61, v[66:67], off nt
